# v99 + XCD leader issues its buffer_inv sc1 together with its buffer_wbl2 (the whole XCD is quiescent once its last workgroup has arrived), none on the post-release path
# speedup vs baseline: 1.0013x; 1.0013x over previous
.LBB0_43:
	s_andn2_saveexec_b64 s[12:13], s[12:13]
	s_cbranch_execz .LBB0_63
	s_mov_b64 s[12:13], exec
	buffer_wbl2 sc1
	buffer_inv sc1
	s_waitcnt lgkmcnt(0)
	s_waitcnt vmcnt(0)
	v_mbcnt_lo_u32_b32 v2, s12, 0
	v_mbcnt_hi_u32_b32 v2, s13, v2
	v_cmp_eq_u32_e32 vcc, 0, v2
	s_and_saveexec_b64 s[14:15], vcc
	s_cbranch_execz .LBB0_46
	s_bcnt1_i32_b64 s11, s[12:13]
	v_mov_b32_e32 v3, 0x3000
	v_mov_b32_e32 v4, s11
	global_atomic_add v3, v3, v4, s[4:5] offset:1024 sc0

.LBB0_60:
	s_or_b64 exec, exec, s[4:5]
	s_mov_b64 s[4:5], exec
	v_mbcnt_lo_u32_b32 v1, s4, 0
	v_mbcnt_hi_u32_b32 v1, s5, v1
	v_cmp_eq_u32_e32 vcc, 0, v1
	s_waitcnt vmcnt(0)
	s_and_saveexec_b64 s[12:13], vcc
	s_cbranch_execz .LBB0_62
	s_bcnt1_i32_b64 s4, s[4:5]
	v_mov_b32_e32 v1, 0x2000
	v_mov_b32_e32 v2, s4
	global_atomic_add v1, v2, s[6:7] offset:1024

.LBB0_195:
	s_andn2_saveexec_b64 s[12:13], s[12:13]
	s_cbranch_execz .LBB0_215
	s_mov_b64 s[12:13], exec
	buffer_wbl2 sc1
	buffer_inv sc1
	s_waitcnt lgkmcnt(0)
	s_waitcnt vmcnt(0)
	v_mbcnt_lo_u32_b32 v2, s12, 0
	v_mbcnt_hi_u32_b32 v2, s13, v2
	v_cmp_eq_u32_e32 vcc, 0, v2
	s_and_saveexec_b64 s[14:15], vcc
	s_cbranch_execz .LBB0_198
	s_bcnt1_i32_b64 s11, s[12:13]
	v_mov_b32_e32 v3, 0x3000
	v_mov_b32_e32 v4, s11
	global_atomic_add v3, v3, v4, s[6:7] offset:1024 sc0

.LBB0_212:
	s_or_b64 exec, exec, s[6:7]
	s_mov_b64 s[6:7], exec
	v_mbcnt_lo_u32_b32 v1, s6, 0
	v_mbcnt_hi_u32_b32 v1, s7, v1
	v_cmp_eq_u32_e32 vcc, 0, v1
	s_waitcnt vmcnt(0)
	s_and_saveexec_b64 s[12:13], vcc
	s_cbranch_execz .LBB0_214
	s_bcnt1_i32_b64 s6, s[6:7]
	v_mov_b32_e32 v1, 0x2000
	v_mov_b32_e32 v2, s6
	global_atomic_add v1, v2, s[8:9] offset:1024

.LBB0_277:
	s_or_b64 exec, exec, s[4:5]
	s_mov_b64 s[4:5], exec
	v_mbcnt_lo_u32_b32 v1, s4, 0
	v_mbcnt_hi_u32_b32 v1, s5, v1
	v_cmp_eq_u32_e32 vcc, 0, v1
	s_waitcnt vmcnt(0)
	s_and_saveexec_b64 s[12:13], vcc
	s_cbranch_execz .LBB0_279
	s_bcnt1_i32_b64 s4, s[4:5]
	v_mov_b32_e32 v1, 0x2000
	v_mov_b32_e32 v2, s4
	global_atomic_add v1, v2, s[8:9] offset:1024

.LBB0_397:
	s_andn2_saveexec_b64 s[8:9], s[8:9]
	s_cbranch_execz .LBB0_417
	s_mov_b64 s[8:9], exec
	buffer_wbl2 sc1
	buffer_inv sc1
	s_waitcnt lgkmcnt(0)
	s_waitcnt vmcnt(0)
	v_mbcnt_lo_u32_b32 v2, s8, 0
	v_mbcnt_hi_u32_b32 v2, s9, v2
	v_cmp_eq_u32_e32 vcc, 0, v2
	s_and_saveexec_b64 s[12:13], vcc
	s_cbranch_execz .LBB0_400
	s_bcnt1_i32_b64 s8, s[8:9]
	v_mov_b32_e32 v3, 0x3000
	v_mov_b32_e32 v4, s8
	global_atomic_add v3, v3, v4, s[4:5] offset:1024 sc0

.LBB0_414:
	s_or_b64 exec, exec, s[4:5]
	s_mov_b64 s[4:5], exec
	v_mbcnt_lo_u32_b32 v1, s4, 0
	v_mbcnt_hi_u32_b32 v1, s5, v1
	v_cmp_eq_u32_e32 vcc, 0, v1
	s_waitcnt vmcnt(0)
	s_and_saveexec_b64 s[8:9], vcc
	s_cbranch_execz .LBB0_416
	s_bcnt1_i32_b64 s4, s[4:5]
	v_mov_b32_e32 v1, 0x2000
	v_mov_b32_e32 v2, s4
	global_atomic_add v1, v2, s[6:7] offset:1024

.LBB0_1056:
	s_andn2_saveexec_b64 s[8:9], s[8:9]
	s_cbranch_execz .LBB0_1076
	s_mov_b64 s[8:9], exec
	buffer_wbl2 sc1
	buffer_inv sc1
	s_waitcnt lgkmcnt(0)
	s_waitcnt vmcnt(0)
	v_mbcnt_lo_u32_b32 v2, s8, 0
	v_mbcnt_hi_u32_b32 v2, s9, v2
	v_cmp_eq_u32_e32 vcc, 0, v2
	s_and_saveexec_b64 s[14:15], vcc
	s_cbranch_execz .LBB0_1059
	s_bcnt1_i32_b64 s8, s[8:9]
	v_mov_b32_e32 v3, 0x3000
	v_mov_b32_e32 v4, s8
	global_atomic_add v3, v3, v4, s[4:5] offset:1024 sc0
